# attention: first half-step's next-tile K/V/bias loads hoisted to the top of the step into their own registers (full-step prefetch distance instead of half)
# baseline (speedup 1.0000x reference)
; __device__ __forceinline__ void finishSM(f32x16& p0, f32x16& p1, float alpha, float& l_reg, bf16x8& pa0, bf16x8& pa1, bf16x8& pa2, bf16x8& pa3) {
; #pragma unroll
;     for (int r = 0; r < 16; ++r) p1[r] = __builtin_amdgcn_exp2f(p1[r]);
;     float ps = 0;
; #pragma unroll
;     for (int r = 0; r < 16; ++r) ps += p0[r];
; #pragma unroll
;     for (int r = 0; r < 16; ++r) ps += p1[r];
;     { auto rr = __builtin_amdgcn_permlane32_swap(__float_as_uint(ps), __float_as_uint(ps), false, false);
;       ps = __uint_as_float(rr[0]) + __uint_as_float(rr[1]); }
;     l_reg = l_reg * alpha + ps;
;     ...
;     PK4(p0, 0, pa0); PK4(p0, 8, pa1); PK4(p1, 0, pa2); PK4(p1, 8, pa3);
; template <int KB>
; __device__ __forceinline__ void qkt(f32x16& p0, f32x16& p1, const char* K_lds, const float* cb_l, int r32, int hi, qlds_t qL) {
;     { const float* cbt = cb_l + KB * 64 + 4 * hi;
; #pragma unroll
;       for (int g4 = 0; g4 < 4; ++g4) { const f32x4 b0 = *(const f32x4*)(cbt + 8 * g4), b1 = *(const f32x4*)(cbt + 32 + 8 * g4);
; #pragma unroll
;           for (int i = 0; i < 4; ++i) { p0[4 * g4 + i] = b0[i]; p1[4 * g4 + i] = b1[i]; } } }
;     const char* kb[4];
; #pragma unroll
;     for (int dd = 0; dd < 4; ++dd) kb[dd] = K_lds + KB * SHM_K + KSWZ(r32, (dd * 16 + hi * 8) * 2);
; #pragma unroll
;     for (int d0 = 0; d0 < 8; ++d0) { const char* a = kb[d0 & 3] + (d0 >> 2) * 128;
;         bf16x8 b0 = *reinterpret_cast<const bf16x8*>(a);
;         bf16x8 b1 = *reinterpret_cast<const bf16x8*>(a + 32 * 256);
;         const bf16x8 q = qL[d0 * 64];
;         p0 = __builtin_amdgcn_mfma_f32_32x32x16_bf16(b0, q, p0, 0, 0, 0);
;         p1 = __builtin_amdgcn_mfma_f32_32x32x16_bf16(b1, q, p1, 0, 0, 0); }
.LBB0_500:
	s_add_i32 s90, s13, 1
	s_ashr_i32 s91, s90, 31
	s_lshl_b64 s[40:41], s[90:91], 8
	s_add_u32 s56, s48, s40
	s_addc_u32 s57, s49, s41
	s_add_u32 s40, s46, s40
	v_lshl_add_u64 v[228:229], s[56:57], 0, v[138:139]
	s_addc_u32 s41, s47, s41
	v_add_co_u32_e32 v232, vcc, s60, v228
	v_lshl_add_u64 v[242:243], s[40:41], 0, v[138:139]
	s_nop 0
	v_addc_co_u32_e32 v233, vcc, 0, v229, vcc
	v_add_co_u32_e32 v246, vcc, s60, v242
	global_load_dwordx4 v[228:231], v[228:229], off
	s_nop 0
	global_load_dwordx4 v[232:235], v[232:233], off
	v_addc_co_u32_e32 v247, vcc, 0, v243, vcc
	global_load_dwordx4 v[242:245], v[242:243], off
	global_load_dwordx4 v[246:249], v[246:247], off
	v_lshl_add_u64 v[250:251], s[90:91], 2, v[168:169]
	global_load_dword v250, v[250:251], off
	v_add_u32_e32 v92, 0x10900, v183
	ds_read_b128 v[64:67], v92
	ds_read_b128 v[68:71], v92 offset:32
	ds_read_b128 v[80:83], v92 offset:128
	ds_read_b128 v[84:87], v92 offset:160
	ds_read_b128 v[72:75], v92 offset:64
	ds_read_b128 v[88:91], v92 offset:192
	ds_read_b128 v[76:79], v92 offset:96
	ds_read_b128 v[92:95], v92 offset:224
	s_waitcnt vmcnt(9)
	ds_read_b128 v[112:115], v182 offset:49152
	s_waitcnt vmcnt(7)
	ds_read_b128 v[116:119], v182 offset:57344
	ds_read_b128 v[120:123], v167
	v_exp_f32_e32 v102, v102
	v_exp_f32_e32 v103, v103
	v_exp_f32_e32 v100, v100
	v_exp_f32_e32 v101, v101
	s_waitcnt lgkmcnt(0)
	v_mfma_f32_32x32x16_bf16 v[80:95], v[116:119], v[120:123], v[80:95]
	v_exp_f32_e32 v98, v98
	v_exp_f32_e32 v99, v99
	v_exp_f32_e32 v96, v96
	v_exp_f32_e32 v97, v97
	v_mfma_f32_32x32x16_bf16 v[64:79], v[112:115], v[120:123], v[64:79]
	ds_read_b128 v[112:115], v181 offset:49152
	ds_read_b128 v[116:119], v181 offset:57344
	ds_read_b128 v[120:123], v167 offset:1024
	s_waitcnt lgkmcnt(0)
	v_mfma_f32_32x32x16_bf16 v[80:95], v[116:119], v[120:123], v[80:95]
	v_mfma_f32_32x32x16_bf16 v[64:79], v[112:115], v[120:123], v[64:79]
	ds_read_b128 v[112:115], v180 offset:49152
	ds_read_b128 v[116:119], v180 offset:57344
	ds_read_b128 v[120:123], v167 offset:2048
	s_waitcnt lgkmcnt(0)
	v_mfma_f32_32x32x16_bf16 v[80:95], v[116:119], v[120:123], v[80:95]
	v_mfma_f32_32x32x16_bf16 v[64:79], v[112:115], v[120:123], v[64:79]
	ds_read_b128 v[112:115], v179 offset:49152
	ds_read_b128 v[116:119], v179 offset:57344
	ds_read_b128 v[120:123], v167 offset:3072
	s_waitcnt lgkmcnt(0)
	v_mfma_f32_32x32x16_bf16 v[80:95], v[116:119], v[120:123], v[80:95]
	v_mfma_f32_32x32x16_bf16 v[64:79], v[112:115], v[120:123], v[64:79]
	ds_read_b128 v[112:115], v182 offset:49280
	ds_read_b128 v[116:119], v182 offset:57472
	ds_read_b128 v[120:123], v167 offset:4096
	s_waitcnt lgkmcnt(0)
	v_mfma_f32_32x32x16_bf16 v[80:95], v[116:119], v[120:123], v[80:95]
	v_mfma_f32_32x32x16_bf16 v[64:79], v[112:115], v[120:123], v[64:79]
	ds_read_b128 v[112:115], v181 offset:49280
	ds_read_b128 v[116:119], v181 offset:57472
	ds_read_b128 v[120:123], v167 offset:5120
	s_waitcnt lgkmcnt(0)
	v_mfma_f32_32x32x16_bf16 v[80:95], v[116:119], v[120:123], v[80:95]
	v_mfma_f32_32x32x16_bf16 v[64:79], v[112:115], v[120:123], v[64:79]
	ds_read_b128 v[112:115], v180 offset:49280
	ds_read_b128 v[116:119], v180 offset:57472
	ds_read_b128 v[120:123], v167 offset:6144
	s_waitcnt lgkmcnt(0)
	v_mfma_f32_32x32x16_bf16 v[80:95], v[116:119], v[120:123], v[80:95]
	v_mfma_f32_32x32x16_bf16 v[64:79], v[112:115], v[120:123], v[64:79]
	ds_read_b128 v[112:115], v179 offset:49280
	ds_read_b128 v[116:119], v179 offset:57472
	ds_read_b128 v[120:123], v167 offset:7168
	s_waitcnt lgkmcnt(0)
	v_mfma_f32_32x32x16_bf16 v[80:95], v[116:119], v[120:123], v[80:95]
	v_exp_f32_e32 v118, v104
	v_add_f32_e32 v104, 0, v219
	v_add_f32_e32 v104, v221, v104
	v_add_f32_e32 v104, v217, v104
	v_add_f32_e32 v104, v220, v104
	v_add_f32_e32 v104, v215, v104
	v_add_f32_e32 v104, v218, v104
	v_add_f32_e32 v104, v214, v104
	v_add_f32_e32 v104, v216, v104
	v_add_f32_e32 v104, v209, v104
	v_add_f32_e32 v104, v212, v104
	v_add_f32_e32 v104, v207, v104
	v_add_f32_e32 v104, v210, v104
	v_mfma_f32_32x32x16_bf16 v[64:79], v[112:115], v[120:123], v[64:79]
	v_exp_f32_e32 v112, v106
	v_add_f32_e32 v104, v137, v104
	v_exp_f32_e32 v113, v107
	v_add_f32_e32 v104, v213, v104
	v_exp_f32_e32 v114, v108
	v_add_f32_e32 v104, v208, v104
	v_exp_f32_e32 v115, v109
	v_add_f32_e32 v104, v211, v104
	v_exp_f32_e32 v116, v110
	v_add_f32_e32 v104, v112, v104
	v_exp_f32_e32 v117, v111
	v_add_f32_e32 v104, v113, v104
	v_add_f32_e32 v104, v114, v104
	v_exp_f32_e32 v119, v105
	v_add_f32_e32 v104, v115, v104
	v_add_f32_e32 v104, v116, v104
	v_add_f32_e32 v104, v117, v104
	v_add_f32_e32 v104, v118, v104
	v_add_f32_e32 v104, v119, v104
	v_add_f32_e32 v104, v102, v104
	v_add_f32_e32 v104, v103, v104
	v_add_f32_e32 v104, v100, v104
	v_add_f32_e32 v104, v101, v104
	v_add_f32_e32 v104, v98, v104
	v_add_f32_e32 v104, v99, v104
	v_add_f32_e32 v104, v96, v104
	v_add_f32_e32 v191, v97, v104
	v_mov_b32_e32 v197, v191
	s_nop 1
	v_permlane32_swap_b32_e32 v191, v197
	v_cvt_pk_bf16_f32 v104, v219, v221
	v_cvt_pk_bf16_f32 v105, v217, v220
	v_cvt_pk_bf16_f32 v106, v215, v218
	v_cvt_pk_bf16_f32 v107, v214, v216
	v_cvt_pk_bf16_f32 v108, v209, v212
	v_cvt_pk_bf16_f32 v109, v207, v210
	v_cvt_pk_bf16_f32 v110, v137, v213
	v_cvt_pk_bf16_f32 v111, v208, v211
	v_cvt_pk_bf16_f32 v112, v112, v113
	v_cvt_pk_bf16_f32 v113, v114, v115
	v_cvt_pk_bf16_f32 v114, v116, v117
	v_cvt_pk_bf16_f32 v115, v118, v119
	v_cvt_pk_bf16_f32 v116, v102, v103
	v_cvt_pk_bf16_f32 v117, v100, v101
	v_cvt_pk_bf16_f32 v118, v98, v99
	v_cvt_pk_bf16_f32 v119, v96, v97
	s_nop 0
	v_permlane32_swap_b32_e32 v104, v106
	v_permlane32_swap_b32_e32 v105, v107
	v_permlane32_swap_b32_e32 v108, v110
	v_permlane32_swap_b32_e32 v109, v111
	v_permlane32_swap_b32_e32 v112, v114
	v_permlane32_swap_b32_e32 v113, v115
	v_permlane32_swap_b32_e32 v116, v118
	v_permlane32_swap_b32_e32 v117, v119
	ds_read_b64_tr_b16 v[120:121], v177 offset:0
	ds_read_b64_tr_b16 v[122:123], v177 offset:0x800
	s_waitcnt vmcnt(6)
; __device__ __forceinline__ void mask_tile(f32x16& p0, f32x16& p1, int dq, unsigned W) {
;     const float NEG = -__builtin_inff();
; #pragma unroll
;     for (int r = 0; r < 16; ++r) {
;         const int c = (r & 3) + 8 * (r >> 2);
;         if ((unsigned)(dq - c) >= W) p0[r] = NEG;
;         if ((unsigned)(dq - c - 32) >= W) p1[r] = NEG;
;     }
; template <int VB>
; __device__ __forceinline__ void pv_tile(f32x16* o, int vb0, bf16x8 pa0, bf16x8 pa1, bf16x8 pa2, bf16x8 pa3) {
;     ...
;     PV_D0(0); PV_D0(1); PV_D0(2); PV_D0(3);
	ds_read_b64_tr_b16 v[124:125], v177 offset:0x1000
	ds_read_b64_tr_b16 v[126:127], v177 offset:0x1800
	ds_read_b64_tr_b16 v[128:129], v177 offset:0x2000
	ds_read_b64_tr_b16 v[130:131], v177 offset:0x2800
	ds_read_b64_tr_b16 v[132:133], v177 offset:0x3000
	ds_read_b64_tr_b16 v[134:135], v177 offset:0x3800
	s_waitcnt lgkmcnt(0)
	v_mfma_f32_32x32x16_bf16 v[48:63], v[104:107], v[120:123], v[48:63]
	ds_read_b64_tr_b16 v[120:121], v177 offset:0x200
	ds_read_b64_tr_b16 v[122:123], v177 offset:0xa00
	v_mfma_f32_32x32x16_bf16 v[48:63], v[108:111], v[124:127], v[48:63]
	ds_read_b64_tr_b16 v[124:125], v177 offset:0x1200
	ds_read_b64_tr_b16 v[126:127], v177 offset:0x1a00
	v_mfma_f32_32x32x16_bf16 v[48:63], v[112:115], v[128:131], v[48:63]
	ds_read_b64_tr_b16 v[128:129], v177 offset:0x2200
	ds_read_b64_tr_b16 v[130:131], v177 offset:0x2a00
	v_mfma_f32_32x32x16_bf16 v[48:63], v[116:119], v[132:135], v[48:63]
	ds_read_b64_tr_b16 v[132:133], v177 offset:0x3200
	ds_read_b64_tr_b16 v[134:135], v177 offset:0x3a00
	s_waitcnt lgkmcnt(0)
	v_mfma_f32_32x32x16_bf16 v[32:47], v[104:107], v[120:123], v[32:47]
	ds_read_b64_tr_b16 v[120:121], v177 offset:0x400
	ds_read_b64_tr_b16 v[122:123], v177 offset:0xc00
	v_mfma_f32_32x32x16_bf16 v[32:47], v[108:111], v[124:127], v[32:47]
	ds_read_b64_tr_b16 v[124:125], v177 offset:0x1400
	ds_read_b64_tr_b16 v[126:127], v177 offset:0x1c00
	v_mfma_f32_32x32x16_bf16 v[32:47], v[112:115], v[128:131], v[32:47]
	ds_read_b64_tr_b16 v[128:129], v177 offset:0x2400
	ds_read_b64_tr_b16 v[130:131], v177 offset:0x2c00
	v_mfma_f32_32x32x16_bf16 v[32:47], v[116:119], v[132:135], v[32:47]
	ds_read_b64_tr_b16 v[132:133], v177 offset:0x3400
	ds_read_b64_tr_b16 v[134:135], v177 offset:0x3c00
	s_waitcnt lgkmcnt(0)
	v_mfma_f32_32x32x16_bf16 v[16:31], v[104:107], v[120:123], v[16:31]
	ds_read_b64_tr_b16 v[120:121], v177 offset:0x600
	ds_read_b64_tr_b16 v[122:123], v177 offset:0xe00
	v_mfma_f32_32x32x16_bf16 v[16:31], v[108:111], v[124:127], v[16:31]
	ds_read_b64_tr_b16 v[124:125], v177 offset:0x1600
	ds_read_b64_tr_b16 v[126:127], v177 offset:0x1e00
	v_mfma_f32_32x32x16_bf16 v[16:31], v[112:115], v[128:131], v[16:31]
	ds_read_b64_tr_b16 v[128:129], v177 offset:0x2600
	ds_read_b64_tr_b16 v[130:131], v177 offset:0x2e00
	v_mfma_f32_32x32x16_bf16 v[16:31], v[116:119], v[132:135], v[16:31]
	ds_read_b64_tr_b16 v[132:133], v177 offset:0x3600
	ds_read_b64_tr_b16 v[134:135], v177 offset:0x3e00
	s_waitcnt lgkmcnt(0)
	v_mfma_f32_32x32x16_bf16 v[0:15], v[104:107], v[120:123], v[0:15]
	s_sub_i32 s6, s13, 63
	s_cmp_le_i32 s13, s1
	s_cselect_b64 s[40:41], -1, 0
	s_cmp_gt_i32 s6, s92
	s_cselect_b64 s[56:57], -1, 0
	s_and_b64 s[40:41], s[40:41], s[56:57]
	s_and_b64 vcc, exec, s[40:41]
	v_mfma_f32_32x32x16_bf16 v[0:15], v[108:111], v[124:127], v[0:15]
	v_mfma_f32_32x32x16_bf16 v[0:15], v[112:115], v[128:131], v[0:15]
	v_mfma_f32_32x32x16_bf16 v[0:15], v[116:119], v[132:135], v[0:15]
	s_cbranch_vccnz .LBB0_502
	v_add_u32_e32 v104, 0x207b, v190
	v_cmp_gt_u32_e32 vcc, s60, v104
	v_add_u32_e32 v104, 0x5b, v190
	s_nop 0
	v_cndmask_b32_e32 v64, v241, v64, vcc
	v_cmp_lt_u32_e32 vcc, s35, v104
	v_add_u32_e32 v104, 0x7a, v190
	s_nop 0
	v_cndmask_b32_e32 v80, v241, v80, vcc
	v_cmp_lt_u32_e32 vcc, s35, v104
	v_add_u32_e32 v104, 0x5a, v190
	s_nop 0
	v_cndmask_b32_e32 v65, v241, v65, vcc
	v_cmp_lt_u32_e32 vcc, s35, v104
	v_add_u32_e32 v104, 0x79, v190
	s_nop 0
	v_cndmask_b32_e32 v81, v241, v81, vcc
	v_cmp_lt_u32_e32 vcc, s35, v104
	v_add_u32_e32 v104, 0x59, v190
	s_nop 0
	v_cndmask_b32_e32 v66, v241, v66, vcc
	v_cmp_lt_u32_e32 vcc, s35, v104
	v_add_u32_e32 v104, 0x78, v190
	s_nop 0
	v_cndmask_b32_e32 v82, v241, v82, vcc
	v_cmp_lt_u32_e32 vcc, s35, v104
	v_add_u32_e32 v104, 0x58, v190
	s_nop 0
	v_cndmask_b32_e32 v67, v241, v67, vcc
	v_cmp_lt_u32_e32 vcc, s35, v104
	v_add_u32_e32 v104, 0x73, v190
	s_nop 0
	v_cndmask_b32_e32 v83, v241, v83, vcc
	v_cmp_lt_u32_e32 vcc, s35, v104
	v_add_u32_e32 v104, 0x53, v190
	s_nop 0
	v_cndmask_b32_e32 v68, v241, v68, vcc
	v_cmp_lt_u32_e32 vcc, s35, v104
	v_add_u32_e32 v104, 0x72, v190
	s_nop 0
	v_cndmask_b32_e32 v84, v241, v84, vcc
	v_cmp_lt_u32_e32 vcc, s35, v104
	v_add_u32_e32 v104, 0x52, v190
	s_nop 0
	v_cndmask_b32_e32 v69, v241, v69, vcc
	v_cmp_lt_u32_e32 vcc, s35, v104
	v_add_u32_e32 v104, 0x71, v190
	s_nop 0
	v_cndmask_b32_e32 v85, v241, v85, vcc
	v_cmp_lt_u32_e32 vcc, s35, v104
	v_add_u32_e32 v104, 0x51, v190
	s_nop 0
	v_cndmask_b32_e32 v70, v241, v70, vcc
	v_cmp_lt_u32_e32 vcc, s35, v104
	v_add_u32_e32 v104, 0x70, v190
	s_nop 0
	v_cndmask_b32_e32 v86, v241, v86, vcc
	v_cmp_lt_u32_e32 vcc, s35, v104
	v_add_u32_e32 v104, 0x50, v190
	s_nop 0
	v_cndmask_b32_e32 v71, v241, v71, vcc
	v_cmp_lt_u32_e32 vcc, s35, v104
	v_add_u32_e32 v104, 0x6b, v190
	s_nop 0
	v_cndmask_b32_e32 v87, v241, v87, vcc
	v_cmp_lt_u32_e32 vcc, s35, v104
	v_add_u32_e32 v104, 0x4b, v190
	s_nop 0
	v_cndmask_b32_e32 v72, v241, v72, vcc
	v_cmp_lt_u32_e32 vcc, s35, v104
	v_add_u32_e32 v104, 0x6a, v190
	s_nop 0
	v_cndmask_b32_e32 v88, v241, v88, vcc
	v_cmp_lt_u32_e32 vcc, s35, v104
	v_add_u32_e32 v104, 0x4a, v190
	s_nop 0
	v_cndmask_b32_e32 v73, v241, v73, vcc
	v_cmp_lt_u32_e32 vcc, s35, v104
	v_add_u32_e32 v104, 0x69, v190
	s_nop 0
	v_cndmask_b32_e32 v89, v241, v89, vcc
	v_cmp_lt_u32_e32 vcc, s35, v104
	v_add_u32_e32 v104, 0x49, v190
	s_nop 0
	v_cndmask_b32_e32 v74, v241, v74, vcc
	v_cmp_lt_u32_e32 vcc, s35, v104
	v_add_u32_e32 v104, 0x68, v190
	s_nop 0
	v_cndmask_b32_e32 v90, v241, v90, vcc
	v_cmp_lt_u32_e32 vcc, s35, v104
	v_add_u32_e32 v104, 0x48, v190
	s_nop 0
	v_cndmask_b32_e32 v75, v241, v75, vcc
	v_cmp_lt_u32_e32 vcc, s35, v104
	v_add_u32_e32 v104, 0x63, v190
	s_nop 0
	v_cndmask_b32_e32 v91, v241, v91, vcc
	v_cmp_lt_u32_e32 vcc, s35, v104
	v_add_u32_e32 v104, 0x43, v190
	s_nop 0
	v_cndmask_b32_e32 v76, v241, v76, vcc
	v_cmp_lt_u32_e32 vcc, s35, v104
	v_add_u32_e32 v104, 0x62, v190
	s_nop 0
	v_cndmask_b32_e32 v92, v241, v92, vcc
	v_cmp_lt_u32_e32 vcc, s35, v104
	v_add_u32_e32 v104, 0x42, v190
	s_nop 0
	v_cndmask_b32_e32 v77, v241, v77, vcc
	v_cmp_lt_u32_e32 vcc, s35, v104
	v_add_u32_e32 v104, 0x61, v190
	s_nop 0
	v_cndmask_b32_e32 v93, v241, v93, vcc
	v_cmp_lt_u32_e32 vcc, s35, v104
	v_add_u32_e32 v104, 0x41, v190
	s_nop 0
	v_cndmask_b32_e32 v78, v241, v78, vcc
	v_cmp_lt_u32_e32 vcc, s35, v104
	v_add_u32_e32 v104, 0x60, v190
	s_nop 0
	v_cndmask_b32_e32 v94, v241, v94, vcc
	v_cmp_lt_u32_e32 vcc, s35, v104
	v_add_u32_e32 v104, 64, v190
	s_nop 0
	v_cndmask_b32_e32 v79, v241, v79, vcc
	v_cmp_lt_u32_e32 vcc, s35, v104
	s_nop 1
	v_cndmask_b32_e32 v95, v241, v95, vcc
; __device__ __forceinline__ void partialSM(f32x16& p0, f32x16& p1, float& m_reg, float& mn, float& alpha) {
;     float pmax = p0[0];
; #pragma unroll
;     for (int r = 1; r < 16; ++r) pmax = fmaxf(pmax, p0[r]);
; #pragma unroll
;     for (int r = 0; r < 16; ++r) pmax = fmaxf(pmax, p1[r]);
;     { auto rr = __builtin_amdgcn_permlane32_swap(__float_as_uint(pmax), __float_as_uint(pmax), false, false);
;       pmax = fmaxf(__uint_as_float(rr[0]), __uint_as_float(rr[1])); }
;     if (__builtin_expect(__all((pmax - m_reg) <= THR2), 1)) { mn = m_reg; alpha = 1.f; }
;     else { mn = fmaxf(m_reg, pmax); alpha = __builtin_amdgcn_exp2f(m_reg - mn); m_reg = mn; }
.LBB0_502:
	v_max_f32_e32 v104, v65, v65
	v_max_f32_e32 v105, v64, v64
	v_max_f32_e32 v104, v105, v104
	v_max3_f32 v104, v104, v66, v67
	v_max3_f32 v104, v104, v68, v69
	v_max3_f32 v104, v104, v70, v71
	v_max3_f32 v104, v104, v72, v73
	v_max3_f32 v104, v104, v74, v75
	v_max3_f32 v104, v104, v76, v77
	v_max3_f32 v104, v104, v78, v79
	v_max3_f32 v104, v104, v80, v81
	v_max3_f32 v104, v104, v82, v83
	v_max3_f32 v104, v104, v84, v85
	v_max3_f32 v104, v104, v86, v87
	v_max3_f32 v104, v104, v88, v89
	v_max3_f32 v104, v104, v90, v91
	v_max3_f32 v104, v104, v92, v93
	v_max3_f32 v104, v104, v94, v95
	v_mov_b32_e32 v105, v104
	s_nop 1
	v_permlane32_swap_b32_e32 v104, v105
	v_max_f32_e32 v105, v105, v105
	v_max_f32_e32 v104, v104, v104
	v_max_f32_e32 v104, v104, v105
	v_sub_f32_e32 v105, v104, v188
	v_cmp_ge_f32_e32 vcc, s89, v105
	v_max_f32_e32 v105, v188, v188
	v_max_f32_e32 v104, v105, v104
	v_sub_f32_e32 v105, v188, v104
	v_exp_f32_e32 v105, v105
	s_cmp_eq_u64 vcc, exec
	s_cselect_b64 s[40:41], -1, 0
	s_barrier
	s_waitcnt vmcnt(0)
	v_cndmask_b32_e64 v206, v105, 1.0, s[40:41]
	v_cmp_gt_f32_e32 vcc, 1.0, v206
	s_waitcnt vmcnt(4)
	ds_write_b128 v184, v[228:231]
	s_waitcnt vmcnt(3)
	ds_write_b128 v185, v[232:235]
	s_waitcnt vmcnt(2)
	ds_write_b128 v174, v[242:245] offset:32768
	s_waitcnt vmcnt(1)
	ds_write_b128 v174, v[246:249] offset:40960
	s_waitcnt vmcnt(0)
	ds_write_b32 v189, v250
	s_cbranch_vccz .LBB0_506
	s_and_saveexec_b64 s[56:57], s[38:39]
	ds_write_b32 v176, v206 offset:128
	s_or_b64 exec, exec, s[56:57]
	s_waitcnt lgkmcnt(0)
	ds_read_b128 v[106:109], v175 offset:224
	ds_read_b128 v[110:113], v175 offset:192
	ds_read_b128 v[114:117], v175 offset:160
	ds_read_b128 v[118:121], v175 offset:128
	s_waitcnt lgkmcnt(3)
	v_pk_mul_f32 v[62:63], v[62:63], v[108:109]
	s_waitcnt lgkmcnt(2)
	v_pk_mul_f32 v[58:59], v[58:59], v[112:113]
	s_waitcnt lgkmcnt(1)
	v_pk_mul_f32 v[54:55], v[54:55], v[116:117]
	s_waitcnt lgkmcnt(0)
	v_pk_mul_f32 v[50:51], v[50:51], v[120:121]
	v_pk_mul_f32 v[60:61], v[60:61], v[106:107]
	v_pk_mul_f32 v[56:57], v[56:57], v[110:111]
	v_pk_mul_f32 v[52:53], v[52:53], v[114:115]
	v_pk_mul_f32 v[48:49], v[48:49], v[118:119]
	v_pk_mul_f32 v[46:47], v[46:47], v[108:109]
	v_pk_mul_f32 v[42:43], v[42:43], v[112:113]
	v_pk_mul_f32 v[38:39], v[38:39], v[116:117]
	v_pk_mul_f32 v[34:35], v[34:35], v[120:121]
	v_pk_mul_f32 v[44:45], v[44:45], v[106:107]
	v_pk_mul_f32 v[40:41], v[40:41], v[110:111]
	v_pk_mul_f32 v[36:37], v[36:37], v[114:115]
	v_pk_mul_f32 v[32:33], v[32:33], v[118:119]
	v_pk_mul_f32 v[30:31], v[30:31], v[108:109]
	v_pk_mul_f32 v[26:27], v[26:27], v[112:113]
	v_pk_mul_f32 v[22:23], v[22:23], v[116:117]
	v_pk_mul_f32 v[18:19], v[18:19], v[120:121]
	v_pk_mul_f32 v[28:29], v[28:29], v[106:107]
	v_pk_mul_f32 v[24:25], v[24:25], v[110:111]
	v_pk_mul_f32 v[20:21], v[20:21], v[114:115]
	v_pk_mul_f32 v[16:17], v[16:17], v[118:119]
	v_pk_mul_f32 v[14:15], v[14:15], v[108:109]
	v_pk_mul_f32 v[10:11], v[10:11], v[112:113]
	v_pk_mul_f32 v[6:7], v[6:7], v[116:117]
	v_pk_mul_f32 v[2:3], v[2:3], v[120:121]
	v_pk_mul_f32 v[12:13], v[12:13], v[106:107]
	v_pk_mul_f32 v[8:9], v[8:9], v[110:111]
	v_pk_mul_f32 v[4:5], v[4:5], v[114:115]
	v_pk_mul_f32 v[0:1], v[0:1], v[118:119]
